# grid barrier tail rewritten: single cross-XCD arrival counter polled by every workgroup (no returning add, no release word, no relay); plus hand-written gdn final stage
# speedup vs baseline: 1.0123x; 1.0097x over previous
; __device__ __forceinline__ unsigned xb_ld(unsigned* p)              { return __hip_atomic_load(p, __ATOMIC_RELAXED, __HIP_MEMORY_SCOPE_AGENT); }
; __device__ __forceinline__ unsigned xb_add(unsigned* p, unsigned v) { return __hip_atomic_fetch_add(p, v, __ATOMIC_RELAXED, __HIP_MEMORY_SCOPE_AGENT); }
; #define XB_SPIN(cond, bar) do { unsigned _sp = 0; while (cond) { __builtin_amdgcn_s_sleep(1); \
;     if ((++_sp & 255u) == 0u) { if (xb_ld(&(bar)[XB_TMO])) break; if (_sp > XB_SPIN_CAP) { atomicAdd(&(bar)[XB_TMO], 1u); break; } } } } while (0)
; __device__ __forceinline__ void xcd_barrier(const XcdBarrier& b) {
;     ...
;         const unsigned old = xb_add(&bar[XB_XSUB(b.x)], 1u);
;         const unsigned gen = old / nloc;
;         if (old + 1u == (gen + 1u) * nloc) {
;             __builtin_amdgcn_fence(__ATOMIC_RELEASE, "agent");
;             asm volatile("s_waitcnt vmcnt(0)" ::: "memory");
;             const unsigned og = xb_add(&bar[XB_TOP], 1u);
;             const unsigned tg = og / nx;
;             if (og + 1u == (tg + 1u) * nx) xb_add(&bar[XB_TOPGEN], 1u);
;             else XB_SPIN(xb_ld(&bar[XB_TOPGEN]) == tg, bar);
.LBB0_194:
	s_or_b64 exec, exec, s[8:9]
	v_cvt_f32_u32_e32 v10, v8
	s_waitcnt vmcnt(0)
	v_readfirstlane_b32 s6, v9
	v_sub_u32_e32 v9, 0, v8
	v_rcp_iflag_f32_e32 v10, v10
	v_add_u32_e32 v11, s6, v7
	v_mul_f32_e32 v10, 0x4f7ffffe, v10
	v_cvt_u32_f32_e32 v10, v10
	v_mul_lo_u32 v7, v9, v10
	v_mul_hi_u32 v7, v10, v7
	v_add_u32_e32 v7, v10, v7
	v_mul_hi_u32 v7, v11, v7
	v_mul_lo_u32 v9, v7, v8
	v_sub_u32_e32 v9, v11, v9
	v_add_u32_e32 v10, 1, v7
	v_cmp_ge_u32_e32 vcc, v9, v8
	s_nop 1
	v_cndmask_b32_e32 v7, v7, v10, vcc
	v_sub_u32_e32 v10, v9, v8
	v_cndmask_b32_e32 v9, v9, v10, vcc
	v_add_u32_e32 v10, 1, v7
	v_cmp_ge_u32_e32 vcc, v9, v8
	v_add_u32_e32 v9, 1, v11
	s_nop 0
	v_cndmask_b32_e32 v7, v7, v10, vcc
	v_mul_lo_u32 v10, v8, v7
	v_add_u32_e32 v8, v10, v8
	v_cmp_ne_u32_e32 vcc, v9, v8
	v_mad_u32_u24 v12, v7, v6, v6
	v_readlane_b32 s8, v252, 33
	v_readlane_b32 s9, v252, 34
	s_mov_b32 s6, 0
	s_waitcnt lgkmcnt(0)
	s_nop 1
	s_cbranch_vccnz .Lgs0_poll
	buffer_wbl2 sc1
	s_waitcnt vmcnt(0)
	global_atomic_add v157, v228, s[8:9]

; __device__ __forceinline__ unsigned xb_ld(unsigned* p)              { return __hip_atomic_load(p, __ATOMIC_RELAXED, __HIP_MEMORY_SCOPE_AGENT); }
; __device__ __forceinline__ unsigned xb_add(unsigned* p, unsigned v) { return __hip_atomic_fetch_add(p, v, __ATOMIC_RELAXED, __HIP_MEMORY_SCOPE_AGENT); }
; #define XB_SPIN(cond, bar) do { unsigned _sp = 0; while (cond) { __builtin_amdgcn_s_sleep(1); \
;     if ((++_sp & 255u) == 0u) { if (xb_ld(&(bar)[XB_TMO])) break; if (_sp > XB_SPIN_CAP) { atomicAdd(&(bar)[XB_TMO], 1u); break; } } } } while (0)
; __device__ __forceinline__ void xcd_barrier(const XcdBarrier& b) {
;     ...
;         const unsigned old = xb_add(&bar[XB_XSUB(b.x)], 1u);
;         const unsigned gen = old / nloc;
;         if (old + 1u == (gen + 1u) * nloc) {
;             __builtin_amdgcn_fence(__ATOMIC_RELEASE, "agent");
;             asm volatile("s_waitcnt vmcnt(0)" ::: "memory");
;             const unsigned og = xb_add(&bar[XB_TOP], 1u);
;             const unsigned tg = og / nx;
;             if (og + 1u == (tg + 1u) * nx) xb_add(&bar[XB_TOPGEN], 1u);
;             else XB_SPIN(xb_ld(&bar[XB_TOPGEN]) == tg, bar);
;             __builtin_amdgcn_fence(__ATOMIC_ACQUIRE, "agent");
;             xb_add(&bar[XB_XGEN(b.x)], 1u);
;             asm volatile("s_waitcnt vmcnt(0)" ::: "memory");
;         } else {
;             XB_SPIN(xb_ld(&bar[XB_XGEN(b.x)]) == gen, bar);
;             __builtin_amdgcn_fence(__ATOMIC_ACQUIRE, "agent");
;             asm volatile("s_waitcnt vmcnt(0)" ::: "memory");
;         }
;     }
;     __syncthreads();
.Lgs0_loop:
	global_load_dword v6, v157, s[8:9] sc1
	s_waitcnt vmcnt(0)
	v_cmp_ge_u32_e32 vcc, v6, v12
	s_cbranch_vccnz .Lgs0_done
	s_sleep 1
	s_add_i32 s6, s6, 1
	s_cmp_lt_u32 s6, 0x8000
	s_cbranch_scc1 .Lgs0_loop
.Lgs0_done:
	s_waitcnt vmcnt(0)
	s_branch .Lgs0_pad
	s_nop 0
	s_nop 0
	s_nop 0
	s_nop 0
	s_nop 0
	s_nop 0
	s_nop 0
	s_nop 0
	s_nop 0
	s_nop 0
	s_nop 0
	s_nop 0
	s_nop 0
	s_nop 0
	s_nop 0
	s_nop 0
	s_nop 0
	s_nop 0
	s_nop 0
	s_nop 0
	s_nop 0
	s_nop 0
	s_nop 0
	s_nop 0
	s_nop 0
	s_nop 0
	s_nop 0
	s_nop 0
	s_nop 0
	s_nop 0
	s_nop 0
	s_nop 0
	s_nop 0
	s_nop 0
	s_nop 0
	s_nop 0
	s_nop 0
	s_nop 0
	s_nop 0
	s_nop 0
	s_nop 0
	s_nop 0
	s_nop 0
	s_nop 0
	s_nop 0
	s_nop 0
	s_nop 0
	s_nop 0
	s_nop 0
	s_nop 0
	s_nop 0
	s_nop 0
	s_nop 0
	s_nop 0
	s_nop 0
	s_nop 0
	s_nop 0
	s_nop 0
	s_nop 0
	s_nop 0
	s_nop 0
	s_nop 0
	s_nop 0
	s_nop 0
	s_nop 0
	s_nop 0
	s_nop 0
	s_nop 0
	s_nop 0
	s_nop 0
	s_nop 0
	s_nop 0
	s_nop 0
	s_nop 0
	s_nop 0
	s_nop 0
	s_nop 0
	s_nop 0
	s_nop 0
	s_nop 0
	s_nop 0
	s_nop 0
	s_nop 0
	s_nop 0
	s_nop 0
	s_nop 0
	s_nop 0
	s_nop 0
	s_nop 0
	s_nop 0
	s_nop 0
	s_nop 0
	s_nop 0
	s_nop 0
	s_nop 0
	s_nop 0
	s_nop 0
	s_nop 0
	s_nop 0
	s_nop 0
	s_nop 0
	s_nop 0
	s_nop 0
	s_nop 0
	s_nop 0
	s_nop 0
	s_nop 0
	s_nop 0
	s_nop 0
	s_nop 0
	s_nop 0
	s_nop 0
	s_nop 0
	s_nop 0
	s_nop 0
	s_nop 0
	s_nop 0
	s_nop 0
	s_nop 0
	s_nop 0
	s_nop 0
	s_nop 0
	s_nop 0
	s_nop 0
	s_nop 0
	s_nop 0
	s_nop 0
	s_nop 0
	s_nop 0
	s_nop 0
	s_nop 0
	s_nop 0
	s_nop 0
	s_nop 0
	s_nop 0
	s_nop 0
	s_nop 0
	s_nop 0
	s_nop 0
	s_nop 0
	s_nop 0
	s_nop 0
	s_nop 0
	s_nop 0
	s_nop 0
	s_nop 0
	s_nop 0
	s_nop 0
	s_nop 0
	s_nop 0
	s_nop 0
	s_nop 0
	s_nop 0
	s_nop 0
	s_nop 0
	s_nop 0
	s_nop 0
	s_nop 0
	s_nop 0
	s_nop 0
	s_nop 0
	s_nop 0
	s_nop 0
	s_nop 0
	s_nop 0
	s_nop 0
	s_nop 0
	s_nop 0
	s_nop 0
	s_nop 0
	s_nop 0
	s_nop 0
	s_nop 0
	s_nop 0
	s_nop 0
	s_nop 0
	s_nop 0
	s_nop 0
	s_nop 0
	s_nop 0
	s_nop 0
	s_nop 0
	s_nop 0
	s_nop 0
	s_nop 0
	s_nop 0
	s_nop 0
	s_nop 0
	s_nop 0
	s_nop 0
	s_nop 0
	s_nop 0
	s_nop 0
	s_nop 0
	s_nop 0
	s_nop 0
.Lgs0_pad:
.LBB0_228:
	s_or_b64 exec, exec, s[0:1]
	s_xor_b64 s[0:1], s[26:27], -1
	v_writelane_b32 v255, s0, 30
	s_waitcnt lgkmcnt(0)
	v_mov_b32_e32 v6, v224
	v_writelane_b32 v255, s1, 31
	s_barrier
	v_readlane_b32 s0, v255, 1
	s_nop 1
	v_add_u32_e32 v6, s0, v6
	s_mov_b32 s0, 0x8000
	v_cmp_gt_i32_e32 vcc, s0, v6
	s_and_saveexec_b64 s[0:1], vcc
	s_cbranch_execz .LBB0_231
	v_ashrrev_i32_e32 v7, 31, v6
	v_lshl_add_u64 v[8:9], v[6:7], 2, s[72:73]
	s_mov_b64 s[4:5], 0

; __device__ __forceinline__ float bf2f(bf16_t b) { return __uint_as_float((unsigned)b << 16); }
; __device__ __forceinline__ bf16_t f2bf(float f) { return (bf16_t)(pk2(f, 0.f) & 0xffffu); }
; __device__ __forceinline__ float fexp(float x) { return __expf(x); }
; __device__ __forceinline__ void gdn_unit(const Ctx& X, LAS unsigned char* hl, int b, int c, int h, int tid_h, int w4, int lane, int layer) {
;     ...
;     {
;         f32x4 acc[4];
;         const float eG63 = fexp(Gs[63]);
; #pragma unroll
;         for (int ct = 0; ct < 4; ++ct) acc[ct] = mma16(P, 16 * w4, WT, 16 * ct, (f32x4){0.f, 0.f, 0.f, 0.f}, r, q);
;         bf16_t* qe = WSP(bf16_t, WS_QEFF) + (size_t)uid * 4096;
; #pragma unroll
;         for (int ct = 0; ct < 4; ++ct)
; #pragma unroll
;             for (int j = 0; j < 4; ++j) { const int ii = 16 * w4 + 4 * q + j, col = 16 * ct + r;
;                 qe[ii * 64 + col] = f2bf(bf2f(Q[ii * LT + col]) * fexp(Gs[ii]) - acc[ct][j]); }
; #pragma unroll
;         for (int ct = 0; ct < 4; ++ct) acc[ct] = mma16(P, 16 * w4, UT, 16 * ct, (f32x4){0.f, 0.f, 0.f, 0.f}, r, q);
;         store_oloc(WSP(bf16_t, WS_OLOC), uid, w4, lane, acc);
; #pragma unroll
;         for (int ct = 0; ct < 4; ++ct) acc[ct] = mma16(KDT, 16 * w4, WT, 16 * ct, (f32x4){0.f, 0.f, 0.f, 0.f}, r, q);
;         bf16_t* mm = WSP(bf16_t, WS_MM) + (size_t)(uid - 2048) * 4096;
; #pragma unroll
;         for (int ct = 0; ct < 4; ++ct)
; #pragma unroll
;             for (int j = 0; j < 4; ++j) { const int ii = 16 * w4 + 4 * q + j, col = 16 * ct + r;
;                 mm[((w4 * 2 + (ct >> 1)) * 64 + (r >> 2) * 16 + 4 * q + j) * 8 + (ct & 1) * 4 + (r & 3)] = f2bf((ii == col ? eG63 : 0.f) - acc[ct][j]); }
; #pragma unroll
;         for (int ct = 0; ct < 4; ++ct) acc[ct] = mma16(KDT, 16 * w4, UT, 16 * ct, (f32x4){0.f, 0.f, 0.f, 0.f}, r, q);
;         store_bc(WSP(bf16_t, WS_BCS), uid, w4, r, q, acc);
;     }
.LBB0_619:
	s_waitcnt lgkmcnt(0)
	s_barrier
	v_bfe_u32 v54, v224, 6, 2
	v_and_b32_e32 v55, 15, v232
	v_lshrrev_b32_e32 v56, 4, v232
	v_lshl_or_b32 v57, v54, 4, v55
	v_mul_u32_u24_e32 v58, 0x90, v57
	v_mul_u32_u24_e32 v59, 0x90, v55
	v_lshl_add_u32 v60, v56, 4, v58
	v_lshl_add_u32 v61, v56, 4, v59
	v_add_u32_e32 v60, v182, v60
	v_add_u32_e32 v61, v182, v61
	v_add_u32_e32 v178, 0xb400, v60
	v_add_u32_e32 v179, 0x4800, v61
	v_add_u32_e32 v60, 0x9000, v60
	v_add_u32_e32 v61, 0x6c00, v61
	ds_read_b128 v[6:9], v178
	ds_read_b128 v[10:13], v178 offset:64
	ds_read_b128 v[22:25], v179
	ds_read_b128 v[26:29], v179 offset:64
	ds_read_b128 v[30:33], v179 offset:2304
	ds_read_b128 v[34:37], v179 offset:2368
	ds_read_b128 v[38:41], v179 offset:4608
	ds_read_b128 v[42:45], v179 offset:4672
	ds_read_b128 v[46:49], v179 offset:6912
	ds_read_b128 v[50:53], v179 offset:6976
	ds_read_b128 v[14:17], v60
	ds_read_b128 v[18:21], v60 offset:64
	v_lshl_add_u32 v62, v57, 2, v185
	v_lshl_add_u32 v63, v56, 3, v58
	v_add_u32_e32 v63, v182, v63
	ds_read_b32 v176, v62
	ds_read_b32 v177, v185 offset:252
	s_lshl_b32 s0, s22, 9
	s_lshl_b32 s1, s23, 7
	s_add_i32 s1, s1, s0
	s_or_b32 s0, s1, s21
	s_ashr_i32 s1, s0, 31
	s_lshl_b64 s[0:1], s[0:1], 13
	s_add_u32 s4, s89, s0
	s_addc_u32 s5, s78, s1
	s_add_u32 s6, s79, s0
	s_addc_u32 s7, s80, s1
	v_readlane_b32 s98, v253, 3
	v_readlane_b32 s99, v253, 4
	s_add_u32 s98, s98, s0
	s_addc_u32 s99, s99, s1
	s_add_u32 s98, s98, 0xff000000
	s_addc_u32 s99, s99, -1
	s_add_u32 s100, s74, s0
	s_addc_u32 s101, s75, s1
	v_readfirstlane_b32 s32, v54
	v_lshlrev_b32_e32 v64, 11, v54
	v_lshlrev_b32_e32 v65, 5, v232
	v_lshl_add_u32 v64, v232, 4, v64
	v_lshlrev_b32_e32 v66, 9, v54
	v_lshl_add_u32 v66, v232, 3, v66
	v_add_u32_e32 v67, 0x1000, v66
	v_lshlrev_b32_e32 v71, 7, v57
	v_lshl_add_u32 v71, v56, 3, v71
	v_lshlrev_b32_e32 v70, 2, v56
	v_sub_u32_e32 v70, v55, v70
	s_waitcnt lgkmcnt(4)
	v_mfma_f32_16x16x32_bf16 v[134:137], v[22:25], v[6:9], 0
	v_mfma_f32_16x16x32_bf16 v[138:141], v[30:33], v[6:9], 0
	v_mfma_f32_16x16x32_bf16 v[142:145], v[38:41], v[6:9], 0
	v_mfma_f32_16x16x32_bf16 v[146:149], v[46:49], v[6:9], 0
	v_mfma_f32_16x16x32_bf16 v[134:137], v[26:29], v[10:13], v[134:137]
	v_mfma_f32_16x16x32_bf16 v[138:141], v[34:37], v[10:13], v[138:141]
	v_mfma_f32_16x16x32_bf16 v[142:145], v[42:45], v[10:13], v[142:145]
	v_mfma_f32_16x16x32_bf16 v[146:149], v[50:53], v[10:13], v[146:149]
	ds_read_b64 v[150:151], v63
	ds_read_b64 v[152:153], v63 offset:32
	ds_read_b64 v[172:173], v63 offset:64
	ds_read_b64 v[174:175], v63 offset:96
	ds_read_b128 v[186:189], v61
	ds_read_b128 v[190:193], v61 offset:64
	ds_read_b128 v[194:197], v61 offset:2304
	ds_read_b128 v[198:201], v61 offset:2368
	ds_read_b128 v[202:205], v61 offset:4608
	ds_read_b128 v[206:209], v61 offset:4672
	ds_read_b128 v[210:213], v61 offset:6912
	s_waitcnt lgkmcnt(13)
	v_mfma_f32_16x16x32_bf16 v[236:239], v[22:25], v[14:17], 0
	v_mfma_f32_16x16x32_bf16 v[240:243], v[30:33], v[14:17], 0
	v_mfma_f32_16x16x32_bf16 v[244:247], v[38:41], v[14:17], 0
	v_mfma_f32_16x16x32_bf16 v[248:251], v[46:49], v[14:17], 0
	v_mfma_f32_16x16x32_bf16 v[236:239], v[26:29], v[18:21], v[236:239]
	v_mfma_f32_16x16x32_bf16 v[240:243], v[34:37], v[18:21], v[240:243]
	v_mfma_f32_16x16x32_bf16 v[244:247], v[42:45], v[18:21], v[244:247]
	v_mfma_f32_16x16x32_bf16 v[248:251], v[50:53], v[18:21], v[248:251]
	ds_read_b128 v[214:217], v61 offset:6976
	s_waitcnt lgkmcnt(8)
	v_mul_f32_e32 v176, 0x3fb8aa3b, v176
	v_mul_f32_e32 v177, 0x3fb8aa3b, v177
	v_exp_f32_e32 v176, v176
	v_exp_f32_e32 v177, v177
	v_cmp_eq_u32_e32 vcc, 0, v70
	v_cmp_eq_u32_e64 s[0:1], 1, v70
	v_lshlrev_b32_e32 v76, 16, v150
	v_and_b32_e32 v77, 0xffff0000, v150
	v_cndmask_b32_e32 v72, 0, v177, vcc
	v_cndmask_b32_e64 v73, 0, v177, s[0:1]
	v_cmp_eq_u32_e32 vcc, 2, v70
	v_cmp_eq_u32_e64 s[0:1], 3, v70
	v_lshlrev_b32_e32 v78, 16, v151
	v_and_b32_e32 v79, 0xffff0000, v151
	v_cndmask_b32_e32 v74, 0, v177, vcc
	v_cndmask_b32_e64 v75, 0, v177, s[0:1]
	s_waitcnt lgkmcnt(0)
	v_mfma_f32_16x16x32_bf16 v[84:87], v[6:9], v[186:189], 0
	v_mfma_f32_16x16x32_bf16 v[88:91], v[6:9], v[194:197], 0
	v_mfma_f32_16x16x32_bf16 v[92:95], v[6:9], v[202:205], 0
	v_mfma_f32_16x16x32_bf16 v[96:99], v[6:9], v[210:213], 0
	v_mfma_f32_16x16x32_bf16 v[114:117], v[14:17], v[186:189], 0
	v_mfma_f32_16x16x32_bf16 v[118:121], v[14:17], v[194:197], 0
	v_mfma_f32_16x16x32_bf16 v[122:125], v[14:17], v[202:205], 0
	v_mfma_f32_16x16x32_bf16 v[126:129], v[14:17], v[210:213], 0
	v_mfma_f32_16x16x32_bf16 v[84:87], v[10:13], v[190:193], v[84:87]
	v_mfma_f32_16x16x32_bf16 v[88:91], v[10:13], v[198:201], v[88:91]
	v_mfma_f32_16x16x32_bf16 v[92:95], v[10:13], v[206:209], v[92:95]
	v_mfma_f32_16x16x32_bf16 v[96:99], v[10:13], v[214:217], v[96:99]
	v_mfma_f32_16x16x32_bf16 v[114:117], v[18:21], v[190:193], v[114:117]
	v_mfma_f32_16x16x32_bf16 v[118:121], v[18:21], v[198:201], v[118:121]
	v_mfma_f32_16x16x32_bf16 v[122:125], v[18:21], v[206:209], v[122:125]
	v_mfma_f32_16x16x32_bf16 v[126:129], v[18:21], v[214:217], v[126:129]
	v_fma_f32 v76, v176, v76, -v134
	v_fma_f32 v77, v176, v77, -v135
	v_fma_f32 v78, v176, v78, -v136
	v_fma_f32 v79, v176, v79, -v137
	v_cvt_pk_bf16_f32 v218, v76, v77
	v_cvt_pk_bf16_f32 v219, v78, v79
	global_store_dwordx2 v71, v[218:219], s[4:5]
	v_lshlrev_b32_e32 v76, 16, v152
	v_and_b32_e32 v77, 0xffff0000, v152
	v_lshlrev_b32_e32 v78, 16, v153
	v_and_b32_e32 v79, 0xffff0000, v153
	v_fma_f32 v76, v176, v76, -v138
	v_fma_f32 v77, v176, v77, -v139
	v_fma_f32 v78, v176, v78, -v140
	v_fma_f32 v79, v176, v79, -v141
	v_cvt_pk_bf16_f32 v220, v76, v77
	v_cvt_pk_bf16_f32 v221, v78, v79
; __device__ __forceinline__ float bf2f(bf16_t b) { return __uint_as_float((unsigned)b << 16); }
; __device__ __forceinline__ bf16_t f2bf(float f) { return (bf16_t)(pk2(f, 0.f) & 0xffffu); }
; __device__ __forceinline__ float fexp(float x) { return __expf(x); }
; #define LBAR() do { asm volatile("s_waitcnt lgkmcnt(0)" ::: "memory"); __builtin_amdgcn_s_barrier(); asm volatile("" ::: "memory"); } while (0)
; __device__ __forceinline__ void gdn_unit(const Ctx& X, LAS unsigned char* hl, int b, int c, int h, int tid_h, int w4, int lane, int layer) {
;     ...
;         bf16_t* qe = WSP(bf16_t, WS_QEFF) + (size_t)uid * 4096;
; #pragma unroll
;         for (int ct = 0; ct < 4; ++ct)
; #pragma unroll
;             for (int j = 0; j < 4; ++j) { const int ii = 16 * w4 + 4 * q + j, col = 16 * ct + r;
;                 qe[ii * 64 + col] = f2bf(bf2f(Q[ii * LT + col]) * fexp(Gs[ii]) - acc[ct][j]); }
; #pragma unroll
;         for (int ct = 0; ct < 4; ++ct) acc[ct] = mma16(P, 16 * w4, UT, 16 * ct, (f32x4){0.f, 0.f, 0.f, 0.f}, r, q);
;         store_oloc(WSP(bf16_t, WS_OLOC), uid, w4, lane, acc);
; #pragma unroll
;         for (int ct = 0; ct < 4; ++ct) acc[ct] = mma16(KDT, 16 * w4, WT, 16 * ct, (f32x4){0.f, 0.f, 0.f, 0.f}, r, q);
;         bf16_t* mm = WSP(bf16_t, WS_MM) + (size_t)(uid - 2048) * 4096;
; #pragma unroll
;         for (int ct = 0; ct < 4; ++ct)
; #pragma unroll
;             for (int j = 0; j < 4; ++j) { const int ii = 16 * w4 + 4 * q + j, col = 16 * ct + r;
;                 mm[((w4 * 2 + (ct >> 1)) * 64 + (r >> 2) * 16 + 4 * q + j) * 8 + (ct & 1) * 4 + (r & 3)] = f2bf((ii == col ? eG63 : 0.f) - acc[ct][j]); }
; #pragma unroll
;         for (int ct = 0; ct < 4; ++ct) acc[ct] = mma16(KDT, 16 * w4, UT, 16 * ct, (f32x4){0.f, 0.f, 0.f, 0.f}, r, q);
;         store_bc(WSP(bf16_t, WS_BCS), uid, w4, r, q, acc);
;     }
;     LBAR();
	global_store_dwordx2 v71, v[220:221], s[4:5] offset:32
	v_lshlrev_b32_e32 v76, 16, v172
	v_and_b32_e32 v77, 0xffff0000, v172
	v_lshlrev_b32_e32 v78, 16, v173
	v_and_b32_e32 v79, 0xffff0000, v173
	v_fma_f32 v76, v176, v76, -v142
	v_fma_f32 v77, v176, v77, -v143
	v_fma_f32 v78, v176, v78, -v144
	v_fma_f32 v79, v176, v79, -v145
	v_cvt_pk_bf16_f32 v222, v76, v77
	v_cvt_pk_bf16_f32 v223, v78, v79
	global_store_dwordx2 v71, v[222:223], s[4:5] offset:64
	v_lshlrev_b32_e32 v76, 16, v174
	v_and_b32_e32 v77, 0xffff0000, v174
	v_lshlrev_b32_e32 v78, 16, v175
	v_and_b32_e32 v79, 0xffff0000, v175
	v_fma_f32 v76, v176, v76, -v146
	v_fma_f32 v77, v176, v77, -v147
	v_fma_f32 v78, v176, v78, -v148
	v_fma_f32 v79, v176, v79, -v149
	v_cvt_pk_bf16_f32 v226, v76, v77
	v_cvt_pk_bf16_f32 v227, v78, v79
	global_store_dwordx2 v71, v[226:227], s[4:5] offset:96
	s_cmp_eq_u32 s32, 0
	s_cselect_b32 s0, 1.0, 0
	v_fma_f32 v76, v72, s0, -v236
	v_fma_f32 v77, v73, s0, -v237
	v_fma_f32 v78, v74, s0, -v238
	v_fma_f32 v79, v75, s0, -v239
	v_cvt_pk_bf16_f32 v100, v76, v77
	v_cvt_pk_bf16_f32 v101, v78, v79
	s_cmp_eq_u32 s32, 1
	s_cselect_b32 s0, 1.0, 0
	v_fma_f32 v76, v72, s0, -v240
	v_fma_f32 v77, v73, s0, -v241
	v_fma_f32 v78, v74, s0, -v242
	v_fma_f32 v79, v75, s0, -v243
	v_cvt_pk_bf16_f32 v102, v76, v77
	v_cvt_pk_bf16_f32 v103, v78, v79
	global_store_dwordx4 v64, v[100:103], s[98:99]
	s_cmp_eq_u32 s32, 2
	s_cselect_b32 s0, 1.0, 0
	v_fma_f32 v76, v72, s0, -v244
	v_fma_f32 v77, v73, s0, -v245
	v_fma_f32 v78, v74, s0, -v246
	v_fma_f32 v79, v75, s0, -v247
	v_cvt_pk_bf16_f32 v104, v76, v77
	v_cvt_pk_bf16_f32 v105, v78, v79
	s_cmp_eq_u32 s32, 3
	s_cselect_b32 s0, 1.0, 0
	v_fma_f32 v76, v72, s0, -v248
	v_fma_f32 v77, v73, s0, -v249
	v_fma_f32 v78, v74, s0, -v250
	v_fma_f32 v79, v75, s0, -v251
	v_cvt_pk_bf16_f32 v106, v76, v77
	v_cvt_pk_bf16_f32 v107, v78, v79
	global_store_dwordx4 v64, v[104:107], s[98:99] offset:1024
	v_cvt_pk_bf16_f32 v108, v84, v85
	v_cvt_pk_bf16_f32 v109, v86, v87
	v_cvt_pk_bf16_f32 v110, v88, v89
	v_cvt_pk_bf16_f32 v111, v90, v91
	global_store_dwordx4 v65, v[108:111], s[6:7] nt
	v_cvt_pk_bf16_f32 v80, v92, v93
	v_cvt_pk_bf16_f32 v81, v94, v95
	v_cvt_pk_bf16_f32 v82, v96, v97
	v_cvt_pk_bf16_f32 v83, v98, v99
	global_store_dwordx4 v65, v[80:83], s[6:7] offset:16 nt
	v_cvt_pk_bf16_f32 v40, v114, v115
	v_cvt_pk_bf16_f32 v41, v116, v117
	global_store_dwordx2 v66, v[40:41], s[100:101]
	v_cvt_pk_bf16_f32 v42, v118, v119
	v_cvt_pk_bf16_f32 v43, v120, v121
	global_store_dwordx2 v66, v[42:43], s[100:101] offset:2048
	v_cvt_pk_bf16_f32 v44, v122, v123
	v_cvt_pk_bf16_f32 v45, v124, v125
	global_store_dwordx2 v67, v[44:45], s[100:101]
	v_cvt_pk_bf16_f32 v46, v126, v127
	v_cvt_pk_bf16_f32 v47, v128, v129
	global_store_dwordx2 v67, v[46:47], s[100:101] offset:2048
	s_branch .Lgdn_p4_pad_end
	s_nop 0
	s_nop 0
	s_nop 0
	s_nop 0
	s_nop 0
	s_nop 0
	s_nop 0
	s_nop 0
	s_nop 0
	s_nop 0
	s_nop 0
	s_nop 0
	s_nop 0
	s_nop 0
	s_nop 0
	s_nop 0
	s_nop 0
	s_nop 0
	s_nop 0
	s_nop 0
	s_nop 0
	s_nop 0
	s_nop 0
	s_nop 0
	s_nop 0
	s_nop 0
	s_nop 0
	s_nop 0
	s_nop 0
	s_nop 0
	s_nop 0
	s_nop 0
	s_nop 0
	s_nop 0
	s_nop 0
	s_nop 0
	s_nop 0
	s_nop 0
	s_nop 0
	s_nop 0
	s_nop 0
	s_nop 0
	s_nop 0
	s_nop 0
	s_nop 0
	s_nop 0
	s_nop 0
	s_nop 0
	s_nop 0
	s_nop 0
	s_nop 0
	s_nop 0
	s_nop 0
	s_nop 0
	s_nop 0
	s_nop 0
	s_nop 0
	s_nop 0
	s_nop 0
	s_nop 0
	s_nop 0
	s_nop 0
	s_nop 0
	s_nop 0
	s_nop 0
	s_nop 0
	s_nop 0
	s_nop 0
	s_nop 0
	s_nop 0
	s_nop 0
	s_nop 0
	s_nop 0
	s_nop 0
	s_nop 0
	s_nop 0
	s_nop 0
	s_nop 0
	s_nop 0
	s_nop 0
	s_nop 0
	s_nop 0
	s_nop 0
	s_nop 0
	s_nop 0
	s_nop 0
	s_nop 0
	s_nop 0
	s_nop 0
	s_nop 0
	s_nop 0
	s_nop 0
	s_nop 0
	s_nop 0
	s_nop 0
	s_nop 0
	s_nop 0
	s_nop 0
	s_nop 0
	s_nop 0
	s_nop 0
	s_nop 0
	s_nop 0
	s_nop 0
	s_nop 0
	s_nop 0
	s_nop 0
	s_nop 0
	s_nop 0
	s_nop 0
	s_nop 0
	s_nop 0
	s_nop 0
	s_nop 0
	s_nop 0
	s_nop 0
	s_nop 0
	s_nop 0
	s_nop 0
	s_nop 0
	s_nop 0
	s_nop 0
	s_nop 0
	s_nop 0
	s_nop 0
	s_nop 0
	s_nop 0
	s_nop 0
	s_nop 0
	s_nop 0
	s_nop 0
	s_nop 0
	s_nop 0
	s_nop 0
	s_nop 0
	s_nop 0
	s_nop 0
	s_nop 0
	s_nop 0
	s_nop 0
	s_nop 0
	s_nop 0
	s_nop 0
	s_nop 0
	s_nop 0
	s_nop 0
	s_nop 0
	s_nop 0
	s_nop 0
	s_nop 0
	s_nop 0
	s_nop 0
	s_nop 0
	s_nop 0
	s_nop 0
	s_nop 0
	s_nop 0
	s_nop 0
	s_nop 0
	s_nop 0
	s_nop 0
	s_nop 0
	s_nop 0
	s_nop 0
	s_nop 0
	s_nop 0
	s_nop 0
	s_nop 0
	s_nop 0
	s_nop 0
	s_nop 0
	s_nop 0
	s_nop 0
	s_nop 0
	s_nop 0
	s_nop 0
	s_nop 0
	s_nop 0
	s_nop 0
	s_nop 0
	s_nop 0
	s_nop 0
	s_nop 0
	s_nop 0
	s_nop 0
	s_nop 0
	s_nop 0
	s_nop 0
	s_nop 0
	s_nop 0
	s_nop 0
	s_nop 0
	s_nop 0
	s_nop 0
	s_nop 0
	s_nop 0
	s_nop 0
	s_nop 0
	s_nop 0
	s_nop 0
	s_nop 0
	s_nop 0
	s_nop 0
	s_nop 0
	s_nop 0
	s_nop 0
	s_nop 0
	s_nop 0
	s_nop 0
	s_nop 0
	s_nop 0
	s_nop 0
	s_nop 0
	s_nop 0
	s_nop 0
	s_nop 0
	s_nop 0
	s_nop 0
	s_nop 0
	s_nop 0
	s_nop 0
	s_nop 0
	s_nop 0
	s_nop 0
	s_nop 0
	s_nop 0
	s_nop 0
	s_nop 0
	s_nop 0
	s_nop 0
	s_nop 0
	s_nop 0
	s_nop 0
	s_nop 0
	s_nop 0
	s_nop 0
	s_nop 0
	s_nop 0
	s_nop 0
	s_nop 0
	s_nop 0
	s_nop 0
	s_nop 0
	s_nop 0
	s_nop 0
	s_nop 0
	s_nop 0
	s_nop 0
	s_nop 0
	s_nop 0
	s_nop 0
	s_nop 0
	s_nop 0
	s_nop 0
	s_nop 0
	s_nop 0
	s_nop 0
	s_nop 0
	s_nop 0
	s_nop 0
	s_nop 0
	s_nop 0
	s_nop 0
	s_nop 0
	s_nop 0
	s_nop 0
	s_nop 0
	s_nop 0
	s_nop 0
	s_nop 0
	s_nop 0
	s_nop 0
	s_nop 0
	s_nop 0
	s_nop 0
	s_nop 0
	s_nop 0
	s_nop 0
	s_nop 0
	s_nop 0
	s_nop 0
	s_nop 0
	s_nop 0
	s_nop 0
	s_nop 0
	s_nop 0
	s_nop 0
	s_nop 0
	s_nop 0
	s_nop 0
	s_nop 0
	s_nop 0
	s_nop 0
	s_nop 0
	s_nop 0
	s_nop 0
	s_nop 0
	s_nop 0
	s_nop 0
	s_nop 0
	s_nop 0
	s_nop 0
	s_nop 0
	s_nop 0
	s_nop 0
	s_nop 0
	s_nop 0
	s_nop 0
	s_nop 0
	s_nop 0
	s_nop 0
	s_nop 0
	s_nop 0
	s_nop 0
	s_nop 0
	s_nop 0
	s_nop 0
	s_nop 0
	s_nop 0
	s_nop 0
	s_nop 0
	s_nop 0
	s_nop 0
	s_nop 0
	s_nop 0
	s_nop 0
	s_nop 0
	s_nop 0
	s_nop 0
	s_nop 0
	s_nop 0
	s_nop 0
	s_nop 0
	s_nop 0
	s_nop 0
	s_nop 0
	s_nop 0
	s_nop 0
	s_nop 0
	s_nop 0
	s_nop 0
	s_nop 0
	s_nop 0

; #define SCAN_LOAD_D(slot, cc) { const int c_ = (cc) < NCH ? (cc) : NCH - 1; const bf16_t* bcn = bc0 + (size_t)c_ * 4096; \
;             _Pragma("unroll") for (int t = 0; t < 4; ++t) { cb[slot][t] = *(const u32x2*)(bcn + 256 * t); cm[slot][t] = mixer == 2 ? *(const f32x4*)(mv0 + (size_t)c_ * 64 + 16 * t) : (f32x4){g64, g64, g64, g64}; } }
; __device__ __forceinline__ void scan_phase(const Ctx& X, int wave, int lane) {
;     ...
;         const int h = bh & 3;
;         const float g64 = __expf(64.0f * log1pf(-exp2f(-5.0f - (float)h)));
;         const float* mv0 = WSP(const float, WS_MVEC) + (size_t)(mixer == 2 ? uid0 - 2 * 2048 : 0) * 64 + 4 * q;
;         u32x2 cb[4][4]; f32x4 cm[4][4];
;     ...
;         SCAN_LOAD_D(0, 0) SCAN_LOAD_D(1, 1) SCAN_LOAD_D(2, 2)
.Lgs1_pad:
.LBB0_675:
	s_or_b64 exec, exec, s[0:1]
	v_readlane_b32 s0, v253, 7
	v_readlane_b32 s1, v253, 8
	s_andn2_b64 vcc, exec, s[0:1]
	s_waitcnt lgkmcnt(0)
	s_barrier
	s_cbranch_vccnz .LBB0_739
	v_mov_b32_e32 v155, v232
	v_readlane_b32 s0, v253, 9
	v_readlane_b32 s4, v253, 14
	v_readlane_b32 s5, v253, 15
	v_add_lshl_u32 v86, v155, s0, 2
	v_readlane_b32 s0, v253, 12
	v_ashrrev_i32_e32 v87, 31, v86
	v_readlane_b32 s1, v253, 13
	s_and_b64 vcc, exec, s[4:5]
	s_nop 0
	v_lshl_add_u64 v[162:163], v[86:87], 1, s[0:1]
	s_mov_b64 s[0:1], -1
	s_cbranch_vccz .LBB0_736
	global_load_dwordx2 v[110:111], v[162:163], off
	v_ashrrev_i32_e32 v6, 2, v155
	s_waitcnt vmcnt(0)
	v_and_b32_e32 v54, -4, v6
	v_readlane_b32 s0, v253, 22
	v_ashrrev_i32_e32 v55, 31, v54
	v_readlane_b32 s1, v253, 23
	v_mov_b32_e32 v38, v0
	v_mov_b32_e32 v39, v0
	v_lshl_add_u64 v[88:89], v[54:55], 2, s[0:1]
	v_readlane_b32 s0, v253, 16
	v_readlane_b32 s1, v253, 17
	s_andn2_b64 vcc, exec, s[0:1]
	s_waitcnt vmcnt(5)
	v_mov_b32_e32 v40, v0
	v_cndmask_b32_e64 v6, 0, 1, s[0:1]
	v_cmp_ne_u32_e64 s[4:5], 1, v6
	v_mov_b32_e32 v41, v0
	s_cbranch_vccnz .LBB0_679
	global_load_dwordx4 v[38:41], v[88:89], off

; #define LAS __attribute__((address_space(3)))
; __device__ __forceinline__ void mixer_out_phase(const Ctx& X, LAS unsigned char* lds, int layer, int tid, int wave, int lane) {
;     constexpr int GP = 264;
;     const bf16_t* proj = WSP(const bf16_t, WS_PROJ);
;     bf16_t* mix = WSP(bf16_t, WS_MIX);
;     for (int u = blockIdx.x; u < 1536; u += gridDim.x) {
;         asm volatile("" : "+v"(lane), "+v"(tid));
;         LAS bf16_t* GT = opq((LAS bf16_t*)lds);
;         const int r = lane & 15, q = lane >> 4, h = wave >> 1, half = wave & 1;
;         const int mixer = u >> 9, rem = u & 511, b = rem >> 7, c = rem & 127;
;         const int uid = unit_id(mixer, b, h, c);
;         const int goff = mixer == 0 ? C_RG : (mixer == 1 ? C_GG : C_HG), moff = mixer == 0 ? 0 : (mixer == 1 ? 512 : 768);
;         const size_t row0 = (size_t)b * T + c * 64;
;         u32x4 gv[4];
; #pragma unroll
;         for (int n = 0; n < 4; ++n) { const int idx = tid + 512 * n; gv[n] = *(const u32x4*)(proj + (row0 + (idx >> 5)) * LDP + goff + (idx & 31) * 8); }
;         const bf16_t* qe = WSP(const bf16_t, WS_QEFF) + (size_t)uid * 4096;
;         const bf16_t* st = WSP(const bf16_t, WS_BCS) + (size_t)uid * 4096;
;         bf16x8 a[2][2], bb[4][2]; u32x4 ov[2][2];
; #pragma unroll
;         for (int rt = 0; rt < 2; ++rt) { const int rt4 = 2 * half + rt;
; #pragma unroll
;             for (int ks = 0; ks < 2; ++ks) a[rt][ks] = *(const bf16x8*)(qe + (16 * rt4 + r) * 64 + ks * 32 + q * 8);
;             const u32x4* ol = (const u32x4*)(WSP(const bf16_t, WS_OLOC) + ((size_t)uid * 4 + rt4) * 1024 + lane * 16); ov[rt][0] = ol[0]; ov[rt][1] = ol[1]; }
; #pragma unroll
;         for (int ct = 0; ct < 4; ++ct)
; #pragma unroll
;             for (int ks = 0; ks < 2; ++ks) { const bf16_t* tb = st + (size_t)((ct * 4 + 2 * ks + (q >> 1)) * 64) * 4;
;                 const u32x2 lo = *(const u32x2*)(tb + ((2 * (q & 1)) * 16 + r) * 4), hi = *(const u32x2*)(tb + ((2 * (q & 1) + 1) * 16 + r) * 4);
;                 bb[ct][ks] = __builtin_bit_cast(bf16x8, (u32x4){lo.x, lo.y, hi.x, hi.y}); }
;         const float* nw = mixer == 0 ? X.in[3] + layer * 256 + h * 64 : (mixer == 1 ? X.in[11] + layer * 64 : X.in[13] + layer * 64);
;         float wv[4];
; #pragma unroll
;         for (int ct = 0; ct < 4; ++ct) wv[ct] = nw[16 * ct + r];
.Lgs2_pad:
.LBB0_886:
	s_or_b64 exec, exec, s[0:1]
	v_readlane_b32 s0, v253, 56
	v_readlane_b32 s1, v253, 57
	s_andn2_b64 vcc, exec, s[0:1]
	s_waitcnt lgkmcnt(0)
	s_barrier
	s_cbranch_vccnz .LBB0_890
	v_readlane_b32 s0, v254, 61
	v_readlane_b32 s1, v254, 62
	s_lshl_b32 s16, s0, 6
	s_lshl_b32 s0, s0, 8
	s_mov_b32 s1, s17
	s_lshl_b64 s[0:1], s[0:1], 2
	v_readlane_b32 s4, v253, 61
	s_add_u32 s8, s4, s0
	v_readlane_b32 s0, v253, 62
	v_readlane_b32 s44, v253, 38
	s_addc_u32 s9, s0, s1
	s_lshl_b64 s[4:5], s[16:17], 2
	v_mov_b32_e32 v104, v224
	v_mov_b32_e32 v105, v232
	s_mov_b32 s10, s2
	v_readlane_b32 s50, v253, 44
	v_readlane_b32 s51, v253, 45
	v_readlane_b32 s54, v253, 48
	v_readlane_b32 s55, v253, 49
	v_readlane_b32 s19, v253, 1
	v_readlane_b32 s20, v253, 2
	v_readlane_b32 s21, v253, 58
	v_readlane_b32 s22, v253, 59
	v_readlane_b32 s23, v253, 60
	v_readlane_b32 s45, v253, 39
	v_readlane_b32 s46, v253, 40
	v_readlane_b32 s47, v253, 41
	v_readlane_b32 s48, v253, 42
	v_readlane_b32 s49, v253, 43
	v_readlane_b32 s52, v253, 46
	v_readlane_b32 s53, v253, 47
	v_readlane_b32 s56, v253, 50
	v_readlane_b32 s57, v253, 51
	v_readlane_b32 s58, v253, 52
	v_readlane_b32 s59, v253, 53

; #define PG8_STAGE(bufoff, gbase, voff) do { _Pragma("unroll") for (int _i = 0; _i < 2; ++_i) \
;         __builtin_amdgcn_global_load_lds((const unsigned*)((const char*)(gbase) + (voff)[_i]), (PG8_LAS unsigned*)(lds + (bufoff) + ldsw + _i * 8192), 16, 0, 0); } while (0)
; #define PG8_BAR __builtin_amdgcn_s_barrier()
; template <class Epi, class Sched, bool ALIGN_EPI = false, bool SP2 = false>
; __device__ __forceinline__ void gemm_phase(PG8_LAS unsigned char* lds, const Gemm g, const Sched& S, const Epi& E) {
;     ...
;     const int tid = tid_, wid = __builtin_amdgcn_readfirstlane(tid >> 6), lane = tid & 63, wr = wid >> 2, wc = wid & 3, fr = lane & 15, fq = lane >> 4;
;     const int K = g.K, nt = K / BK;
;     unsigned voffA[2], voffB[2];
; #pragma unroll
;     for (int i = 0; i < 2; ++i) { int R, C; stage_rc(tid * 16 + i * 8192, R, C); const int Rb = Epi::PERM ? ((R & ~31) + perm32(R & 31)) : R;
;         voffA[i] = (unsigned)(R * K + C) * 2u; voffB[i] = (unsigned)(Rb * K + C) * 2u; }
;     const size_t kstep = (size_t)(BK * 2);
;     const size_t hstep = (size_t)HALF * K * 2;
;     const size_t tstep = 2 * hstep;
;     const unsigned ldsw = (unsigned)wid * 1024u;
;     const int aoff = lds_byte(wr * 64 + fr, fq * 8), boff = lds_byte(wc * 32 + fr, fq * 8);
;     ...
;     Unit cur, nxt; int ui = 0;
;     float rsv[8];
;     if (!S.next(0, cur)) return;
;     f32x4 acc[2][2][4][2];
; #pragma unroll
;     for (int a = 0; a < 2; ++a)
; #pragma unroll
;         for (int b = 0; b < 2; ++b)
; #pragma unroll
;             for (int m = 0; m < 4; ++m)
; #pragma unroll
;                 for (int n = 0; n < 2; ++n) acc[a][b][m][n] = (f32x4){0.f, 0.f, 0.f, 0.f};
;     bf16x8 At[4][2], B0[2][2], B1[2][2];
;     const char* cA = (const char*)g.A + (size_t)cur.pm * tstep; const char* cB = (const char*)g.Bt + (size_t)cur.pn * tstep;
;     S.a_ready(cur);
;     if constexpr (SP2) {
;         PG8_STAGE(PG8_SB(0, 0), cB, voffB); PG8_STAGE(PG8_SB(0, 1), cB + hstep, voffB); PG8_STAGE(PG8_SA(0, 0), cA, voffA); PG8_STAGE(PG8_SA(0, 1), cA + hstep, voffA);
;         if (wr == 1) PG8_BAR;
.Lgs3_pad:
.LBB0_942:
	s_or_b64 exec, exec, s[0:1]
	s_and_b64 s[0:1], s[26:27], exec
	v_readlane_b32 s0, v253, 63
	v_readlane_b32 s1, v254, 0
	s_waitcnt vmcnt(0)
	v_mov_b32_e32 v10, v224
	s_waitcnt lgkmcnt(0)
	v_cndmask_b32_e64 v6, 0, 1, s[0:1]
	v_cmp_ne_u32_e64 s[4:5], 1, v6
	s_barrier
	s_nop 0
	v_writelane_b32 v255, s4, 32
	s_cselect_b32 s35, 0, s29
	s_cselect_b32 s34, 0, s28
	v_writelane_b32 v255, s5, 33
	s_andn2_b64 vcc, exec, s[0:1]
	v_readfirstlane_b32 s6, v10
	s_cbranch_vccnz .LBB0_1042
	v_lshlrev_b32_e32 v6, 4, v10
	v_add_u32_e32 v7, 0x2000, v6
	v_ashrrev_i32_e32 v8, 31, v7
	v_lshrrev_b32_e32 v8, 22, v8
	v_add_u32_e32 v8, v7, v8
	v_ashrrev_i32_e32 v11, 10, v8
	v_mul_i32_i24_e32 v8, 0x400, v11
	v_sub_u32_e32 v7, v7, v8
	v_lshrrev_b32_e32 v8, 4, v7
	v_bitop3_b32 v7, v8, v7, 32 bitop3:0x6c
	v_ashrrev_i32_e32 v8, 31, v7
	v_readlane_b32 s0, v254, 61
	v_lshrrev_b32_e32 v8, 26, v8
	v_readlane_b32 s1, v254, 62
	v_add_u32_e32 v8, v7, v8
	v_lshlrev_b32_e32 v9, 3, v11
	s_lshl_b64 s[0:1], s[0:1], 21
	v_readlane_b32 s4, v253, 54
	v_ashrrev_i32_e32 v12, 6, v8
	v_and_b32_e32 v9, -16, v9
	s_add_u32 s16, s4, s0
	v_readlane_b32 s0, v253, 55
	v_add_u32_e32 v9, v12, v9
	s_addc_u32 s19, s0, s1
	v_and_b32_e32 v13, 3, v12
	s_mov_b32 s0, 0x1fffe0
	v_lshrrev_b32_e32 v14, 2, v9
	v_lshlrev_b32_e32 v15, 1, v9
	v_and_b32_e32 v8, 0xc0, v8
	v_and_or_b32 v13, v9, s0, v13
	v_and_b32_e32 v14, 4, v14
	v_and_b32_e32 v15, 24, v15
	v_sub_u32_e32 v7, v7, v8
	v_or3_b32 v14, v13, v14, v15
	v_lshlrev_b32_e32 v13, 5, v11
	v_ashrrev_i16_sdwa v7, v228, sext(v7) dst_sel:DWORD dst_unused:UNUSED_PAD src0_sel:DWORD src1_sel:BYTE_0
	v_and_b32_e32 v15, 32, v13
	v_bfe_i32 v13, v7, 0, 16
	v_add_lshl_u32 v7, v15, v13, 1
	v_lshl_add_u32 v142, v14, 11, v7
	v_lshl_add_u32 v144, v9, 11, v7
	v_bfe_i32 v7, v10, 27, 1
	v_lshrrev_b32_e32 v7, 22, v7
	v_add_u32_e32 v7, v6, v7
	v_and_b32_e32 v7, 0xfffffc00, v7
	v_sub_u32_e32 v6, v6, v7
	v_lshrrev_b32_e32 v7, 4, v6
	v_ashrrev_i32_e32 v8, 31, v10
	v_bitop3_b32 v6, v7, v6, 32 bitop3:0x6c
	v_lshrrev_b32_e32 v8, 26, v8
	v_ashrrev_i32_e32 v7, 31, v6
	v_add_u32_e32 v8, v10, v8
	v_lshrrev_b32_e32 v7, 26, v7
	v_ashrrev_i32_e32 v15, 6, v8
	v_add_u32_e32 v7, v6, v7
	v_lshlrev_b32_e32 v8, 3, v15
	v_ashrrev_i32_e32 v14, 6, v7
	v_and_b32_e32 v8, -16, v8
	v_add_u32_e32 v8, v14, v8
	v_and_b32_e32 v9, 3, v14
	v_lshrrev_b32_e32 v16, 2, v8
	v_lshlrev_b32_e32 v17, 1, v8
	v_and_b32_e32 v7, 0xc0, v7
	s_ashr_i32 s8, s6, 6
	v_and_or_b32 v9, v8, s0, v9
	v_and_b32_e32 v16, 4, v16
	v_and_b32_e32 v17, 24, v17
	v_sub_u32_e32 v6, v6, v7
	s_ashr_i32 s7, s6, 8
	s_lshl_b32 s33, s8, 10
	v_or3_b32 v9, v9, v16, v17
	v_lshlrev_b32_e32 v16, 5, v15
	v_ashrrev_i16_sdwa v6, v228, sext(v6) dst_sel:DWORD dst_unused:UNUSED_PAD src0_sel:DWORD src1_sel:BYTE_0
	v_readlane_b32 s0, v254, 26
	v_and_b32_e32 v17, 32, v16
	v_bfe_i32 v16, v6, 0, 16
	v_readlane_b32 s1, v254, 27
	s_add_u32 s4, s16, s0
	v_add_lshl_u32 v6, v17, v16, 1
	s_addc_u32 s5, s19, s1
	s_add_i32 s80, s33, 0
	v_lshl_add_u32 v156, v9, 11, v6
	s_add_i32 m0, s80, 0x10000
	v_lshl_add_u32 v146, v8, 11, v6
	global_load_lds_dwordx4 v156, s[4:5]
	s_add_i32 m0, s80, 0x12000
	s_add_u32 s0, s4, 0x40000
	global_load_lds_dwordx4 v142, s[4:5]
	s_addc_u32 s1, s5, 0
	s_add_i32 m0, s80, 0x14000
	s_add_i32 s81, s80, 0x2000
	global_load_lds_dwordx4 v156, s[0:1]
	s_add_i32 m0, s80, 0x16000
	s_add_i32 s87, s80, 0x4000
	global_load_lds_dwordx4 v142, s[0:1]
	v_readlane_b32 s0, v254, 28
	s_mov_b32 m0, s80
	v_readlane_b32 s1, v254, 29
	s_add_i32 s88, s80, 0x6000
	v_mov_b32_e32 v143, v157
	s_cmp_eq_u32 s7, 1
	v_lshl_add_u64 v[6:7], s[4:5], 0, v[156:157]
	v_lshl_add_u64 v[8:9], s[4:5], 0, v[142:143]
	global_load_lds_dwordx4 v146, s[0:1]
	s_mov_b32 m0, s81
	s_nop 0
	global_load_lds_dwordx4 v144, s[0:1]
	v_readlane_b32 s0, v254, 30
	s_mov_b32 m0, s87
	v_readlane_b32 s1, v254, 31
	s_nop 4
	global_load_lds_dwordx4 v146, s[0:1]
	s_mov_b32 m0, s88
	s_nop 0
	global_load_lds_dwordx4 v144, s[0:1]
	s_cselect_b64 s[0:1], -1, 0
	s_cmp_lg_u32 s7, 1
	s_cbranch_scc1 .LBB0_945
	s_barrier

; #define PG8_STAGE(bufoff, gbase, voff) do { _Pragma("unroll") for (int _i = 0; _i < 2; ++_i) \
;         __builtin_amdgcn_global_load_lds((const unsigned*)((const char*)(gbase) + (voff)[_i]), (PG8_LAS unsigned*)(lds + (bufoff) + ldsw + _i * 8192), 16, 0, 0); } while (0)
; #define PG8_BAR __builtin_amdgcn_s_barrier()
; template <class Epi, class Sched, bool ALIGN_EPI = false, bool SP2 = false>
; __device__ __forceinline__ void gemm_phase(PG8_LAS unsigned char* lds, const Gemm g, const Sched& S, const Epi& E) {
;     ...
;     const int tid = tid_, wid = __builtin_amdgcn_readfirstlane(tid >> 6), lane = tid & 63, wr = wid >> 2, wc = wid & 3, fr = lane & 15, fq = lane >> 4;
;     const int K = g.K, nt = K / BK;
;     unsigned voffA[2], voffB[2];
; #pragma unroll
;     for (int i = 0; i < 2; ++i) { int R, C; stage_rc(tid * 16 + i * 8192, R, C); const int Rb = Epi::PERM ? ((R & ~31) + perm32(R & 31)) : R;
;         voffA[i] = (unsigned)(R * K + C) * 2u; voffB[i] = (unsigned)(Rb * K + C) * 2u; }
;     const size_t kstep = (size_t)(BK * 2);
;     const size_t hstep = (size_t)HALF * K * 2;
;     const size_t tstep = 2 * hstep;
;     const unsigned ldsw = (unsigned)wid * 1024u;
;     const int aoff = lds_byte(wr * 64 + fr, fq * 8), boff = lds_byte(wc * 32 + fr, fq * 8);
;     ...
;     Unit cur, nxt; int ui = 0;
;     float rsv[8];
;     if (!S.next(0, cur)) return;
;     f32x4 acc[2][2][4][2];
; #pragma unroll
;     for (int a = 0; a < 2; ++a)
; #pragma unroll
;         for (int b = 0; b < 2; ++b)
; #pragma unroll
;             for (int m = 0; m < 4; ++m)
; #pragma unroll
;                 for (int n = 0; n < 2; ++n) acc[a][b][m][n] = (f32x4){0.f, 0.f, 0.f, 0.f};
;     bf16x8 At[4][2], B0[2][2], B1[2][2];
;     const char* cA = (const char*)g.A + (size_t)cur.pm * tstep; const char* cB = (const char*)g.Bt + (size_t)cur.pn * tstep;
;     S.a_ready(cur);
;     if constexpr (SP2) {
;         PG8_STAGE(PG8_SB(0, 0), cB, voffB); PG8_STAGE(PG8_SB(0, 1), cB + hstep, voffB); PG8_STAGE(PG8_SA(0, 0), cA, voffA); PG8_STAGE(PG8_SA(0, 1), cA + hstep, voffA);
;         if (wr == 1) PG8_BAR;
.Lgs4_pad:
.LBB0_1094:
	s_or_b64 exec, exec, s[0:1]
	v_readlane_b32 s0, v254, 1
	s_waitcnt lgkmcnt(0)
	v_mov_b32_e32 v6, v224
	v_readlane_b32 s1, v254, 2
	s_barrier
	s_andn2_b64 vcc, exec, s[0:1]
	v_readfirstlane_b32 s4, v6
	s_cbranch_vccnz .LBB0_1112
	v_lshlrev_b32_e32 v10, 4, v6
	v_add_u32_e32 v8, 0x2000, v10
	v_ashrrev_i32_e32 v7, 31, v8
	v_lshrrev_b32_e32 v7, 22, v7
	v_add_u32_e32 v7, v8, v7
	v_ashrrev_i32_e32 v7, 10, v7
	v_mul_i32_i24_e32 v9, 0x400, v7
	v_sub_u32_e32 v8, v8, v9
	v_lshrrev_b32_e32 v9, 4, v8
	v_bitop3_b32 v9, v9, v8, 32 bitop3:0x6c
	v_ashrrev_i32_e32 v8, 31, v9
	v_readlane_b32 s0, v254, 61
	v_lshrrev_b32_e32 v8, 26, v8
	v_readlane_b32 s1, v254, 62
	v_add_u32_e32 v11, v9, v8
	v_lshlrev_b32_e32 v12, 3, v7
	s_mul_i32 s0, s0, 0xb00000
	v_readlane_b32 s1, v253, 36
	v_ashrrev_i32_e32 v8, 6, v11
	v_and_b32_e32 v12, -16, v12
	s_add_u32 s16, s1, s0
	v_readlane_b32 s0, v253, 37
	v_add_u32_e32 v12, v8, v12
	s_addc_u32 s78, s0, 0
	v_and_b32_e32 v13, 3, v8
	s_mov_b32 s0, 0x1fffe0
	v_lshrrev_b32_e32 v14, 2, v12
	v_lshlrev_b32_e32 v15, 1, v12
	v_and_b32_e32 v11, 0xc0, v11
	v_and_or_b32 v13, v12, s0, v13
	v_and_b32_e32 v14, 4, v14
	v_and_b32_e32 v15, 24, v15
	v_sub_u32_e32 v9, v9, v11
	v_or3_b32 v13, v13, v14, v15
	v_lshlrev_b32_e32 v14, 5, v7
	v_ashrrev_i16_sdwa v9, v228, sext(v9) dst_sel:DWORD dst_unused:UNUSED_PAD src0_sel:DWORD src1_sel:BYTE_0
	v_and_b32_e32 v14, 32, v14
	v_bfe_i32 v9, v9, 0, 16
	v_add_lshl_u32 v11, v14, v9, 1
	v_lshl_add_u32 v134, v13, 11, v11
	v_lshl_add_u32 v136, v12, 11, v11
	v_bfe_i32 v11, v6, 27, 1
	v_lshrrev_b32_e32 v11, 22, v11
	v_add_u32_e32 v11, v10, v11
	v_and_b32_e32 v11, 0xfffffc00, v11
	v_sub_u32_e32 v10, v10, v11
	v_lshrrev_b32_e32 v11, 4, v10
	v_bitop3_b32 v12, v11, v10, 32 bitop3:0x6c
	v_ashrrev_i32_e32 v11, 31, v6
	v_lshrrev_b32_e32 v11, 26, v11
	v_ashrrev_i32_e32 v10, 31, v12
	v_add_u32_e32 v11, v6, v11
	v_lshrrev_b32_e32 v10, 26, v10
	v_ashrrev_i32_e32 v11, 6, v11
	v_add_u32_e32 v13, v12, v10
	v_lshlrev_b32_e32 v14, 3, v11
	v_ashrrev_i32_e32 v10, 6, v13
	v_and_b32_e32 v14, -16, v14
	v_add_u32_e32 v14, v10, v14
	v_and_b32_e32 v15, 3, v10
	v_lshrrev_b32_e32 v16, 2, v14
	v_lshlrev_b32_e32 v17, 1, v14
	v_and_b32_e32 v13, 0xc0, v13
	s_ashr_i32 s6, s4, 6
	v_and_or_b32 v15, v14, s0, v15
	v_and_b32_e32 v16, 4, v16
	v_and_b32_e32 v17, 24, v17
	v_sub_u32_e32 v12, v12, v13
	s_ashr_i32 s5, s4, 8
	s_lshl_b32 s79, s6, 10
	v_or3_b32 v15, v15, v16, v17
	v_lshlrev_b32_e32 v16, 5, v11
	v_ashrrev_i16_sdwa v12, v228, sext(v12) dst_sel:DWORD dst_unused:UNUSED_PAD src0_sel:DWORD src1_sel:BYTE_0
	v_readlane_b32 s0, v254, 8
	v_and_b32_e32 v16, 32, v16
	v_bfe_i32 v12, v12, 0, 16
	v_readlane_b32 s1, v254, 9
	s_add_u32 s22, s16, s0
	v_add_lshl_u32 v13, v16, v12, 1
	s_addc_u32 s23, s78, s1
	s_add_i32 s87, s79, 0
	v_lshl_add_u32 v156, v15, 11, v13
	s_add_i32 m0, s87, 0x10000
	v_lshl_add_u32 v138, v14, 11, v13
	global_load_lds_dwordx4 v156, s[22:23]
	s_add_i32 m0, s87, 0x12000
	s_add_u32 s0, s22, 0x40000
	global_load_lds_dwordx4 v134, s[22:23]
	s_addc_u32 s1, s23, 0
	s_add_i32 m0, s87, 0x14000
	s_add_i32 s19, s87, 0x2000
	global_load_lds_dwordx4 v156, s[0:1]
	s_add_i32 m0, s87, 0x16000
	s_add_i32 s88, s87, 0x4000
	global_load_lds_dwordx4 v134, s[0:1]
	v_readlane_b32 s0, v254, 14
	s_mov_b32 m0, s87
	v_readlane_b32 s1, v254, 15
	s_add_i32 s89, s87, 0x6000
	s_cmp_eq_u32 s5, 1
	s_nop 2
	global_load_lds_dwordx4 v138, s[0:1]
	s_mov_b32 m0, s19
	s_nop 0
	global_load_lds_dwordx4 v136, s[0:1]
	v_readlane_b32 s0, v254, 16
	s_mov_b32 m0, s88
	v_readlane_b32 s1, v254, 17
	s_nop 4
	global_load_lds_dwordx4 v138, s[0:1]
	s_mov_b32 m0, s89
	s_nop 0
	global_load_lds_dwordx4 v136, s[0:1]
	s_cselect_b64 s[0:1], -1, 0
	s_cmp_lg_u32 s5, 1
	s_cbranch_scc1 .LBB0_1097
	s_barrier

; #define PG8_STAGE(bufoff, gbase, voff) do { _Pragma("unroll") for (int _i = 0; _i < 2; ++_i) \
;         __builtin_amdgcn_global_load_lds((const unsigned*)((const char*)(gbase) + (voff)[_i]), (PG8_LAS unsigned*)(lds + (bufoff) + ldsw + _i * 8192), 16, 0, 0); } while (0)
; #define PG8_BAR __builtin_amdgcn_s_barrier()
; template <class Epi, class Sched, bool ALIGN_EPI = false, bool SP2 = false>
; __device__ __forceinline__ void gemm_phase(PG8_LAS unsigned char* lds, const Gemm g, const Sched& S, const Epi& E) {
;     ...
;     for (int i = 0; i < 2; ++i) { int R, C; stage_rc(tid * 16 + i * 8192, R, C); const int Rb = Epi::PERM ? ((R & ~31) + perm32(R & 31)) : R;
;         voffA[i] = (unsigned)(R * K + C) * 2u; voffB[i] = (unsigned)(Rb * K + C) * 2u; }
;     const size_t kstep = (size_t)(BK * 2);
;     const size_t hstep = (size_t)HALF * K * 2;
;     const size_t tstep = 2 * hstep;
;     const unsigned ldsw = (unsigned)wid * 1024u;
;     const int aoff = lds_byte(wr * 64 + fr, fq * 8), boff = lds_byte(wc * 32 + fr, fq * 8);
;     ...
;     Unit cur, nxt; int ui = 0;
;     float rsv[8];
;     if (!S.next(0, cur)) return;
;     f32x4 acc[2][2][4][2];
; #pragma unroll
;     for (int a = 0; a < 2; ++a)
; #pragma unroll
;         for (int b = 0; b < 2; ++b)
; #pragma unroll
;             for (int m = 0; m < 4; ++m)
; #pragma unroll
;                 for (int n = 0; n < 2; ++n) acc[a][b][m][n] = (f32x4){0.f, 0.f, 0.f, 0.f};
;     bf16x8 At[4][2], B0[2][2], B1[2][2];
;     const char* cA = (const char*)g.A + (size_t)cur.pm * tstep; const char* cB = (const char*)g.Bt + (size_t)cur.pn * tstep;
;     S.a_ready(cur);
;     if constexpr (SP2) {
;         PG8_STAGE(PG8_SB(0, 0), cB, voffB); PG8_STAGE(PG8_SB(0, 1), cB + hstep, voffB); PG8_STAGE(PG8_SA(0, 0), cA, voffA); PG8_STAGE(PG8_SA(0, 1), cA + hstep, voffA);
;         if (wr == 1) PG8_BAR;
.Lgs5_pad:
.LBB0_1164:
	s_or_b64 exec, exec, s[0:1]
	v_readlane_b32 s0, v255, 32
	v_mov_b32_e32 v10, v224
	v_readlane_b32 s1, v255, 33
	s_waitcnt lgkmcnt(0)
	s_barrier
	s_and_b64 vcc, exec, s[0:1]
	v_readfirstlane_b32 s0, v10
	s_cbranch_vccnz .LBB0_1316
	v_lshlrev_b32_e32 v6, 4, v10
	v_add_u32_e32 v7, 0x2000, v6
	v_ashrrev_i32_e32 v8, 31, v7
	v_lshrrev_b32_e32 v8, 22, v8
	v_add_u32_e32 v8, v7, v8
	v_ashrrev_i32_e32 v11, 10, v8
	v_mul_i32_i24_e32 v8, 0x400, v11
	v_sub_u32_e32 v7, v7, v8
	v_lshrrev_b32_e32 v8, 4, v7
	v_bitop3_b32 v7, v8, v7, 32 bitop3:0x6c
	v_ashrrev_i32_e32 v8, 31, v7
	v_lshrrev_b32_e32 v8, 26, v8
	v_add_u32_e32 v8, v7, v8
	v_lshlrev_b32_e32 v9, 3, v11
	v_ashrrev_i32_e32 v12, 6, v8
	v_and_b32_e32 v9, -16, v9
	v_add_u32_e32 v9, v12, v9
	v_and_b32_e32 v13, 3, v12
	s_mov_b32 s6, 0xffffe0
	v_lshrrev_b32_e32 v14, 2, v9
	v_lshlrev_b32_e32 v15, 1, v9
	v_and_or_b32 v13, v9, s6, v13
	v_and_b32_e32 v14, 4, v14
	v_and_b32_e32 v15, 24, v15
	v_and_b32_e32 v8, 0xc0, v8
	v_readlane_b32 s4, v254, 61
	v_or3_b32 v13, v13, v14, v15
	v_sub_u32_e32 v7, v7, v8
	v_readlane_b32 s5, v254, 62
	v_mul_u32_u24_e32 v15, 0xb00, v13
	v_lshlrev_b32_e32 v13, 5, v11
	v_ashrrev_i16_sdwa v7, v228, sext(v7) dst_sel:DWORD dst_unused:UNUSED_PAD src0_sel:DWORD src1_sel:BYTE_0
	v_and_b32_e32 v13, 32, v13
	v_bfe_i32 v14, v7, 0, 16
	s_movk_i32 s5, 0xb00
	v_add_u32_e32 v7, v13, v14
	v_mul_lo_u32 v8, v9, s5
	v_add_lshl_u32 v134, v15, v7, 1
	v_add_lshl_u32 v136, v7, v8, 1
	v_bfe_i32 v7, v10, 27, 1
	v_lshrrev_b32_e32 v7, 22, v7
	v_add_u32_e32 v7, v6, v7
	v_and_b32_e32 v7, 0xfffffc00, v7
	v_sub_u32_e32 v6, v6, v7
	v_lshrrev_b32_e32 v7, 4, v6
	v_ashrrev_i32_e32 v8, 31, v10
	v_bitop3_b32 v6, v7, v6, 32 bitop3:0x6c
	v_lshrrev_b32_e32 v8, 26, v8
	v_ashrrev_i32_e32 v7, 31, v6
	v_add_u32_e32 v8, v10, v8
	v_lshrrev_b32_e32 v7, 26, v7
	v_ashrrev_i32_e32 v16, 6, v8
	v_add_u32_e32 v7, v6, v7
	v_lshlrev_b32_e32 v8, 3, v16
	v_ashrrev_i32_e32 v15, 6, v7
	v_and_b32_e32 v8, -16, v8
	s_mul_i32 s1, s4, 0x580000
	v_readlane_b32 s4, v253, 34
	v_add_u32_e32 v8, v15, v8
	s_add_u32 s16, s4, s1
	v_readlane_b32 s1, v253, 35
	v_and_b32_e32 v9, 3, v15
	v_lshrrev_b32_e32 v17, 2, v8
	v_lshlrev_b32_e32 v18, 1, v8
	v_and_b32_e32 v7, 0xc0, v7
	s_addc_u32 s87, s1, 0
	s_ashr_i32 s4, s0, 6
	v_and_or_b32 v9, v8, s6, v9
	v_and_b32_e32 v17, 4, v17
	v_and_b32_e32 v18, 24, v18
	v_sub_u32_e32 v6, v6, v7
	v_readlane_b32 s6, v254, 11
	s_ashr_i32 s1, s0, 8
	s_lshl_b32 s88, s4, 10
	v_or3_b32 v9, v9, v17, v18
	v_lshlrev_b32_e32 v17, 5, v16
	v_ashrrev_i16_sdwa v6, v228, sext(v6) dst_sel:DWORD dst_unused:UNUSED_PAD src0_sel:DWORD src1_sel:BYTE_0
	v_mul_lo_u32 v7, v8, s5
	s_mul_i32 s5, s6, 0x160000
	v_and_b32_e32 v17, 32, v17
	v_bfe_i32 v18, v6, 0, 16
	s_add_u32 s10, s16, s5
	s_mul_hi_i32 s5, s6, 0x160000
	v_mul_u32_u24_e32 v9, 0xb00, v9
	v_add_u32_e32 v6, v17, v18
	s_addc_u32 s11, s87, s5
	s_add_i32 s89, s88, 0
	v_add_lshl_u32 v156, v9, v6, 1
	s_add_i32 m0, s89, 0x10000
	v_add_lshl_u32 v138, v6, v7, 1
	global_load_lds_dwordx4 v156, s[10:11]
	s_add_i32 m0, s89, 0x12000
	s_add_u32 s6, s10, 0xb0000
	global_load_lds_dwordx4 v134, s[10:11]
	s_addc_u32 s7, s11, 0
	s_add_i32 m0, s89, 0x14000
	s_add_i32 s90, s89, 0x2000
	global_load_lds_dwordx4 v156, s[6:7]
	s_add_i32 m0, s89, 0x16000
	s_add_i32 s91, s89, 0x4000
	global_load_lds_dwordx4 v134, s[6:7]
	v_readlane_b32 s6, v254, 34
	s_mov_b32 m0, s89
	v_readlane_b32 s7, v254, 35
	s_add_i32 s92, s89, 0x6000
	v_mov_b32_e32 v135, v157
	s_cmp_eq_u32 s1, 1
	v_lshl_add_u64 v[6:7], s[10:11], 0, v[156:157]
	s_cselect_b64 s[14:15], -1, 0
	global_load_lds_dwordx4 v138, s[6:7]
	s_mov_b32 m0, s90
	s_cmp_lg_u32 s1, 1
	global_load_lds_dwordx4 v136, s[6:7]
	v_readlane_b32 s6, v254, 36
	s_mov_b32 m0, s91
	v_readlane_b32 s7, v254, 37
	v_lshl_add_u64 v[8:9], s[10:11], 0, v[134:135]
	s_nop 3
	global_load_lds_dwordx4 v138, s[6:7]
	s_mov_b32 m0, s92
	s_nop 0
	global_load_lds_dwordx4 v136, s[6:7]
	s_cbranch_scc1 .LBB0_1167
	s_barrier

; #define GSYNC() do { XcdBarrier b_; b_.bar = WSP(unsigned, WS_CTL); b_.x = xb_xcc_id(); b_.st = (volatile LAS unsigned*)(lds + LDS_BAR_OFF); xcd_barrier(b_); } while (0)
; __device__ __forceinline__ void xcd_barrier(const XcdBarrier& b) {
;     ...
;         }
;     }
;     __syncthreads();
; __global__ void __launch_bounds__(512, 2) fwd_kernel(Ctx X) {
;     ...
;         GSYNC();
;         if (l + 1 == DEPTH) norm_phase(X.out, X.in[19], nullptr, X.out, gw, ngw, lane);
.Lgs6_pad:
.LBB0_1368:
	s_or_b64 exec, exec, s[0:1]
	v_readlane_b32 s0, v254, 57
	v_readlane_b32 s1, v254, 58
	s_andn2_b64 vcc, exec, s[0:1]
	s_waitcnt lgkmcnt(0)
	s_barrier
	s_cbranch_vccz .LBB0_1369
	s_getpc_b64 s[98:99]
